# BN=128 GEMM loops (G2,G3,G5): one workgroup barrier per 32-k slice instead of two, mid-slice barrier and the wave 4-7 half-slice stagger removed
# baseline (speedup 1.0000x reference)
.LBB0_115:
	s_andn2_b64 vcc, exec, s[22:23]
	s_cbranch_vccnz .LBB0_138
	v_readlane_b32 s22, v254, 44
	v_readlane_b32 s23, v254, 45
	s_andn2_b64 vcc, exec, s[22:23]
	s_cbranch_vccnz .LBB0_138
	v_mov_b32_e32 v8, v202
	v_readlane_b32 s8, v254, 48
	v_bfe_u32 v135, v8, 4, 2
	v_bfe_u32 v4, v8, 2, 4
	v_ashrrev_i32_e32 v136, 6, v8
	v_bitop3_b32 v0, v135, v8, 3 bitop3:0x78
	v_or_b32_e32 v9, s8, v4
	v_readlane_b32 s8, v254, 46
	v_lshlrev_b32_e32 v0, 4, v0
	v_cmp_gt_i32_e32 vcc, 16, v136
	v_or_b32_e32 v10, s8, v4
	v_lshl_add_u64 v[2:3], s[20:21], 0, v[0:1]
	v_lshl_add_u64 v[4:5], s[46:47], 0, v[0:1]
	v_lshlrev_b32_e32 v0, 4, v136
	v_cndmask_b32_e32 v11, v9, v10, vcc
	v_cndmask_b32_e32 v7, v3, v5, vcc
	v_cndmask_b32_e32 v6, v2, v4, vcc
	v_add_u32_e32 v11, v11, v0
	v_cmp_gt_i32_e32 vcc, 8, v136
	v_mad_i64_i32 v[126:127], s[20:21], v11, s5, v[6:7]
	s_nop 0
	v_cndmask_b32_e32 v11, v9, v10, vcc
	s_movk_i32 s8, 0x80
	v_cndmask_b32_e32 v7, v3, v5, vcc
	v_cndmask_b32_e32 v6, v2, v4, vcc
	v_add3_u32 v11, v0, v11, s8
	v_cmp_gt_i32_e32 vcc, 0, v136
	v_mad_i64_i32 v[128:129], s[20:21], v11, s5, v[6:7]
	s_nop 0
	v_cndmask_b32_e32 v6, v9, v10, vcc
	s_movk_i32 s8, 0x100
	v_and_b32_e32 v134, 63, v8
	v_cndmask_b32_e32 v3, v3, v5, vcc
	v_cndmask_b32_e32 v2, v2, v4, vcc
	v_add3_u32 v0, v0, v6, s8
	v_mad_i64_i32 v[130:131], s[20:21], v0, s5, v[2:3]
	v_lshlrev_b32_e32 v0, 4, v134
	v_lshl_or_b32 v137, v136, 10, v0
	v_add_u32_e32 v0, 0x2000, v137
	v_readfirstlane_b32 s8, v137
	s_mov_b32 m0, s8
	v_readfirstlane_b32 s8, v0
	v_add_u32_e32 v0, 0x4000, v137
	s_barrier
	global_load_lds_dwordx4 v[126:127], off
	s_mov_b32 m0, s8
	v_readfirstlane_b32 s8, v0
	v_add_u32_e32 v0, 0x6000, v137
	global_load_lds_dwordx4 v[128:129], off
	s_mov_b32 m0, s8
	v_readfirstlane_b32 s8, v0
	v_add_u32_e32 v0, 0x8000, v137
	global_load_lds_dwordx4 v[130:131], off
	v_lshl_add_u64 v[2:3], v[126:127], 0, 64
	s_mov_b32 m0, s8
	v_readfirstlane_b32 s8, v0
	v_add_u32_e32 v0, 0xa000, v137
	global_load_lds_dwordx4 v[2:3], off
	v_lshl_add_u64 v[2:3], v[128:129], 0, 64
	s_mov_b32 m0, s8
	v_readfirstlane_b32 s8, v0
	v_add_u32_e32 v0, 0xc000, v137
	global_load_lds_dwordx4 v[2:3], off
	v_lshl_add_u64 v[2:3], v[130:131], 0, 64
	s_mov_b32 m0, s8
	v_readfirstlane_b32 s8, v0
	v_add_u32_e32 v0, 0xe000, v137
	global_load_lds_dwordx4 v[2:3], off
	v_lshl_add_u64 v[2:3], v[126:127], 0, s[10:11]
	s_mov_b32 m0, s8
	v_readfirstlane_b32 s8, v0
	v_add_u32_e32 v0, 0x10000, v137
	global_load_lds_dwordx4 v[2:3], off
	v_lshl_add_u64 v[2:3], v[128:129], 0, s[10:11]
	s_mov_b32 m0, s8
	v_readfirstlane_b32 s8, v0
	global_load_lds_dwordx4 v[2:3], off
	v_lshl_add_u64 v[2:3], v[130:131], 0, s[10:11]
	s_mov_b32 m0, s8
	v_and_b32_e32 v138, 15, v8
	global_load_lds_dwordx4 v[2:3], off
	v_readfirstlane_b32 s90, v126
	v_readfirstlane_b32 s91, v127
	v_readfirstlane_b32 s92, v130
	v_readfirstlane_b32 s93, v131
	v_readfirstlane_b32 s88, v137
	s_nop 1
	v_subrev_u32_e32 v126, s90, v126
	v_subrev_u32_e32 v128, s90, v128
	v_subrev_u32_e32 v130, s92, v130
	s_add_u32 s90, s90, 0xc0
	s_addc_u32 s91, s91, 0
	s_add_u32 s92, s92, 0xc0
	s_addc_u32 s93, s93, 0
	v_bfe_u32 v2, v8, 2, 2
	v_and_b32_e32 v139, 1, v136
	v_xor_b32_e32 v2, v135, v2
	v_lshlrev_b32_e32 v3, 6, v138
	v_ashrrev_i32_e32 v0, 7, v8
	v_lshl_or_b32 v2, v2, 4, v3
	v_lshlrev_b32_e32 v3, 12, v139
	s_movk_i32 s8, 0x4000
	s_waitcnt vmcnt(9)
	v_mov_b32_e32 v19, 0
	v_mov_b32_e32 v20, 0
	v_mov_b32_e32 v21, 0
	v_mov_b32_e32 v30, 0
	v_mov_b32_e32 v31, 0
	v_mov_b32_e32 v32, 0
	v_mov_b32_e32 v33, 0
	v_mov_b32_e32 v35, 0
	v_mov_b32_e32 v36, 0
	v_mov_b32_e32 v37, 0
	v_mov_b32_e32 v38, 0
	v_mov_b32_e32 v39, 0
	v_mov_b32_e32 v40, 0
	v_mov_b32_e32 v41, 0
	v_mov_b32_e32 v42, 0
	v_mov_b32_e32 v43, 0
	v_mov_b32_e32 v44, 0
	v_mov_b32_e32 v45, 0
	v_mov_b32_e32 v46, 0
	v_mov_b32_e32 v47, 0
	v_mov_b32_e32 v48, 0
	v_mov_b32_e32 v49, 0
	v_mov_b32_e32 v50, 0
	v_mov_b32_e32 v51, 0
	v_mov_b32_e32 v52, 0
	v_mov_b32_e32 v53, 0
	v_mov_b32_e32 v54, 0
	v_mov_b32_e32 v55, 0
	v_mov_b32_e32 v56, 0
	v_mov_b32_e32 v57, 0
	v_mov_b32_e32 v58, 0
	v_mov_b32_e32 v59, 0
	v_mov_b32_e32 v60, 0
	v_mov_b32_e32 v61, 0
	v_mov_b32_e32 v62, 0
	v_mov_b32_e32 v63, 0
	v_mov_b32_e32 v64, 0
	v_mov_b32_e32 v65, 0
	v_mov_b32_e32 v66, 0
	v_mov_b32_e32 v67, 0
	v_mov_b32_e32 v68, 0
	v_mov_b32_e32 v69, 0
	v_mov_b32_e32 v70, 0
	v_mov_b32_e32 v71, 0
	v_mov_b32_e32 v72, 0
	v_mov_b32_e32 v73, 0
	v_mov_b32_e32 v74, 0
	v_mov_b32_e32 v75, 0
	v_mov_b32_e32 v76, 0
	v_mov_b32_e32 v77, 0
	v_mov_b32_e32 v78, 0
	v_mov_b32_e32 v79, 0
	v_mov_b32_e32 v80, 0
	v_mov_b32_e32 v81, 0
	v_mov_b32_e32 v82, 0
	v_mov_b32_e32 v83, 0
	v_mov_b32_e32 v84, 0
	v_mov_b32_e32 v85, 0
	v_mov_b32_e32 v86, 0
	v_mov_b32_e32 v87, 0
	v_mov_b32_e32 v88, 0
	v_mov_b32_e32 v89, 0
	v_mov_b32_e32 v90, 0
	v_mov_b32_e32 v91, 0
	v_mov_b32_e32 v92, 0
	v_mov_b32_e32 v93, 0
	v_mov_b32_e32 v94, 0
	v_mov_b32_e32 v95, 0
	v_mov_b32_e32 v96, 0
	v_mov_b32_e32 v97, 0
	v_mov_b32_e32 v98, 0
	v_mov_b32_e32 v99, 0
	v_mov_b32_e32 v100, 0
	v_mov_b32_e32 v101, 0
	v_mov_b32_e32 v102, 0
	v_mov_b32_e32 v103, 0
	v_mov_b32_e32 v104, 0
	v_mov_b32_e32 v105, 0
	s_waitcnt vmcnt(6)
	v_lshl_or_b32 v140, v0, 12, v2
	v_or3_b32 v141, v3, v2, s8
	s_waitcnt lgkmcnt(0)
	s_barrier
	ds_read_b128 v[2:5], v140
	ds_read_b128 v[6:9], v140 offset:1024
	ds_read_b128 v[10:13], v140 offset:2048
	ds_read_b128 v[14:17], v140 offset:3072
	ds_read_b128 v[26:29], v141
	ds_read_b128 v[22:25], v141 offset:1024
	v_cmp_lt_i32_e32 vcc, 3, v136
	s_and_saveexec_b64 s[20:21], vcc
	s_cbranch_execz .LBB0_119
.LBB0_119:
	s_or_b64 exec, exec, s[20:21]
	v_mov_b32_e32 v18, 0
	v_mov_b32_e32 v34, 0
	v_add_u32_e32 v142, 0x800, v141
	s_mov_b64 s[20:21], 0
	s_mov_b32 s8, 3
	s_branch .LBB0_121

.LBB0_127:
	s_waitcnt lgkmcnt(0)
	s_add_i32 s26, s8, -2
	s_and_b32 s28, s26, 3
	s_mulk_i32 s28, 0x6000
	v_add_u32_e32 v127, s28, v140
	v_add_u32_e32 v143, s28, v141
	ds_read_b128 v[26:29], v143
	v_mfma_f32_16x16x32_bf16 v[74:77], v[2:5], v[106:109], v[74:77]
	ds_read_b128 v[22:25], v143 offset:1024
	v_mfma_f32_16x16x32_bf16 v[58:61], v[6:9], v[106:109], v[58:61]
	ds_read_b128 v[118:121], v127
	v_mfma_f32_16x16x32_bf16 v[38:41], v[10:13], v[106:109], v[38:41]
	ds_read_b128 v[114:117], v127 offset:1024
	v_mfma_f32_16x16x32_bf16 v[30:33], v[14:17], v[106:109], v[30:33]
	ds_read_b128 v[110:113], v127 offset:2048
	ds_read_b128 v[106:109], v127 offset:3072
	v_mfma_f32_16x16x32_bf16 v[94:97], v[2:5], v[144:147], v[94:97]
	v_mfma_f32_16x16x32_bf16 v[82:85], v[6:9], v[144:147], v[82:85]
	v_mfma_f32_16x16x32_bf16 v[66:69], v[10:13], v[144:147], v[66:69]
	v_mfma_f32_16x16x32_bf16 v[34:37], v[14:17], v[144:147], v[34:37]
	s_mov_b64 s[26:27], -1
	s_and_b64 vcc, exec, s[24:25]
	s_cbranch_vccz .LBB0_129
	s_waitcnt vmcnt(0)
	s_mov_b64 s[26:27], 0

.LBB0_133:
	s_waitcnt lgkmcnt(0)
	s_andn2_b64 vcc, exec, s[22:23]
	s_cbranch_vccnz .Lgm_G5x_noread
	s_add_i32 s19, s8, -1
	s_and_b32 s19, s19, 2
	s_mulk_i32 s19, 0x6000
	v_add_u32_e32 v127, s19, v140
	v_add_u32_e32 v132, s19, v141
	ds_read_b128 v[26:29], v132
	v_mfma_f32_16x16x32_bf16 v[74:77], v[118:121], v[144:147], v[74:77]
	ds_read_b128 v[22:25], v132 offset:1024
	v_mfma_f32_16x16x32_bf16 v[58:61], v[114:117], v[144:147], v[58:61]
	ds_read_b128 v[2:5], v127
	v_mfma_f32_16x16x32_bf16 v[38:41], v[110:113], v[144:147], v[38:41]
	ds_read_b128 v[6:9], v127 offset:1024
	v_mfma_f32_16x16x32_bf16 v[30:33], v[106:109], v[144:147], v[30:33]
	ds_read_b128 v[10:13], v127 offset:2048
	ds_read_b128 v[14:17], v127 offset:3072
	s_branch .LBB0_120

.LBB0_135:
	v_cmp_gt_i32_e32 vcc, 4, v136
	s_and_saveexec_b64 s[20:21], vcc
	s_cbranch_execz .LBB0_137
.LBB0_137:
	s_or_b64 exec, exec, s[20:21]
	s_movk_i32 s8, 0x4400
	v_mul_lo_u32 v4, v136, s8
	v_lshl_or_b32 v2, v138, 2, v4
	s_movk_i32 s8, 0x440
	v_mad_u32_u24 v2, v135, s8, v2
	v_add_u32_e32 v5, 0x1000, v2
	v_add_u32_e32 v6, 0x1400, v2
	s_waitcnt vmcnt(0) lgkmcnt(0)
	s_barrier
	ds_write2_b32 v2, v102, v90 offset1:16
	ds_write2_b32 v2, v103, v91 offset0:68 offset1:84
	ds_write2_b32 v2, v104, v92 offset0:136 offset1:152
	ds_write2_b32 v2, v105, v93 offset0:204 offset1:220
	ds_write2_b32 v2, v74, v94 offset0:32 offset1:48
	ds_write2_b32 v2, v75, v95 offset0:100 offset1:116
	ds_write2_b32 v2, v76, v96 offset0:168 offset1:184
	ds_write2_b32 v2, v77, v97 offset0:236 offset1:252
	ds_write2_b32 v5, v98, v78 offset0:64 offset1:80
	ds_write2_b32 v5, v99, v79 offset0:132 offset1:148
	ds_write2_b32 v5, v100, v80 offset0:200 offset1:216
	ds_write2_b32 v6, v101, v81 offset0:12 offset1:28
	ds_write2_b32 v5, v58, v82 offset0:96 offset1:112
	ds_write2_b32 v5, v59, v83 offset0:164 offset1:180
	ds_write2_b32 v5, v60, v84 offset0:232 offset1:248
	ds_write2_b32 v6, v61, v85 offset0:44 offset1:60
	v_add_u32_e32 v5, 0x2000, v2
	v_add_u32_e32 v6, 0x2400, v2
	ds_write2_b32 v5, v86, v62 offset0:128 offset1:144
	ds_write2_b32 v5, v87, v63 offset0:196 offset1:212
	ds_write2_b32 v6, v88, v64 offset0:8 offset1:24
	ds_write2_b32 v6, v89, v65 offset0:76 offset1:92
	ds_write2_b32 v5, v38, v66 offset0:160 offset1:176
	ds_write2_b32 v5, v39, v67 offset0:228 offset1:244
	ds_write2_b32 v6, v40, v68 offset0:40 offset1:56
	ds_write2_b32 v6, v41, v69 offset0:108 offset1:124
	v_add_u32_e32 v5, 0x3000, v2
	v_add_u32_e32 v2, 0x3400, v2
	v_readlane_b32 s8, v254, 46
	ds_write2_b32 v5, v70, v50 offset0:192 offset1:208
	ds_write2_b32 v2, v71, v51 offset0:4 offset1:20
	ds_write2_b32 v2, v72, v52 offset0:72 offset1:88
	ds_write2_b32 v2, v73, v53 offset0:140 offset1:156
	ds_write2_b32 v5, v30, v34 offset0:224 offset1:240
	ds_write2_b32 v2, v31, v35 offset0:36 offset1:52
	ds_write2_b32 v2, v32, v36 offset0:104 offset1:120
	ds_write2_b32 v2, v33, v37 offset0:172 offset1:188
	v_lshl_add_u32 v0, v0, 6, s8
	v_lshrrev_b32_e32 v5, 3, v134
	v_lshlrev_b32_e32 v2, 3, v134
	v_and_b32_e32 v6, 56, v2
	v_or_b32_e32 v2, v0, v5
	v_add_u32_e32 v0, 0xfffff000, v0
	v_lshlrev_b32_e32 v3, 6, v139
	v_readlane_b32 s8, v254, 47
	v_lshrrev_b32_e32 v9, 10, v0
	v_cmp_lt_i32_e32 vcc, s1, v2
	v_or3_b32 v12, v3, s8, v6
	v_mul_u32_u24_e32 v3, 0x110, v5
	v_lshlrev_b32_e32 v5, 2, v6
	v_cndmask_b32_e32 v0, 4, v9, vcc
	s_mul_i32 s8, s18, 5
	v_add3_u32 v8, v4, v3, v5
	v_add_u32_e32 v0, s8, v0
	v_mov_b64_e32 v[4:5], s[14:15]
	v_mad_i64_i32 v[6:7], s[20:21], v0, s82, v[4:5]
	v_lshlrev_b32_e32 v0, 2, v12
	v_ashrrev_i32_e32 v3, 31, v2
	v_lshl_add_u64 v[18:19], v[6:7], 0, v[0:1]
	v_lshlrev_b64 v[6:7], 11, v[2:3]
	v_lshl_add_u64 v[10:11], s[66:67], 0, v[6:7]
	v_lshlrev_b32_e32 v6, 1, v12
	v_mov_b32_e32 v7, v1
	v_lshl_add_u64 v[26:27], v[10:11], 0, v[6:7]
	s_mov_b64 s[22:23], 0x8605000
	v_lshl_add_u64 v[18:19], v[18:19], 0, s[22:23]
	global_load_dwordx4 v[36:39], v[18:19], off
	global_load_dwordx4 v[40:43], v[18:19], off offset:16
	global_load_dwordx4 v[44:47], v[26:27], off
	v_or_b32_e32 v10, 8, v2
	v_ashrrev_i32_e32 v11, 31, v10
	v_lshlrev_b64 v[10:11], 11, v[10:11]
	v_lshl_add_u64 v[10:11], s[66:67], 0, v[10:11]
	v_lshl_add_u64 v[102:103], v[10:11], 0, v[6:7]
	global_load_dwordx4 v[48:51], v[102:103], off
	v_or_b32_e32 v10, 16, v2
	v_ashrrev_i32_e32 v11, 31, v10
	v_lshlrev_b64 v[10:11], 11, v[10:11]
	v_lshl_add_u64 v[10:11], s[66:67], 0, v[10:11]
	v_lshl_add_u64 v[104:105], v[10:11], 0, v[6:7]
	global_load_dwordx4 v[52:55], v[104:105], off
	v_or_b32_e32 v10, 24, v2
	v_ashrrev_i32_e32 v11, 31, v10
	v_lshlrev_b64 v[10:11], 11, v[10:11]
	v_lshl_add_u64 v[10:11], s[66:67], 0, v[10:11]
	v_lshl_add_u64 v[106:107], v[10:11], 0, v[6:7]
	global_load_dwordx4 v[56:59], v[106:107], off
	v_or_b32_e32 v10, 32, v2
	v_ashrrev_i32_e32 v11, 31, v10
	v_lshlrev_b64 v[10:11], 11, v[10:11]
	v_lshl_add_u64 v[10:11], s[66:67], 0, v[10:11]
	v_lshl_add_u64 v[108:109], v[10:11], 0, v[6:7]
	global_load_dwordx4 v[60:63], v[108:109], off
	v_or_b32_e32 v10, 40, v2
	v_ashrrev_i32_e32 v11, 31, v10
	v_lshlrev_b64 v[10:11], 11, v[10:11]
	v_lshl_add_u64 v[10:11], s[66:67], 0, v[10:11]
	v_lshl_add_u64 v[110:111], v[10:11], 0, v[6:7]
	global_load_dwordx4 v[64:67], v[110:111], off
	v_or_b32_e32 v10, 48, v2
	v_ashrrev_i32_e32 v11, 31, v10
	v_lshlrev_b64 v[10:11], 11, v[10:11]
	v_lshl_add_u64 v[10:11], s[66:67], 0, v[10:11]
	v_lshl_add_u64 v[112:113], v[10:11], 0, v[6:7]
	global_load_dwordx4 v[68:71], v[112:113], off
	v_or_b32_e32 v10, 56, v2
	v_ashrrev_i32_e32 v11, 31, v10
	v_lshlrev_b64 v[10:11], 11, v[10:11]
	v_lshl_add_u64 v[10:11], s[66:67], 0, v[10:11]
	v_lshl_add_u64 v[114:115], v[10:11], 0, v[6:7]
	global_load_dwordx4 v[72:75], v[114:115], off
	ds_read_b128 v[84:87], v8
	ds_read_b128 v[88:91], v8 offset:16
	ds_read_b128 v[92:95], v8 offset:2176
	ds_read_b128 v[96:99], v8 offset:2192
	s_waitcnt vmcnt(7)
	v_lshlrev_b32_e32 v116, 16, v44
	v_and_b32_e32 v117, 0xffff0000, v44
	v_lshlrev_b32_e32 v118, 16, v45
	v_and_b32_e32 v119, 0xffff0000, v45
	v_lshlrev_b32_e32 v120, 16, v46
	v_and_b32_e32 v121, 0xffff0000, v46
	v_lshlrev_b32_e32 v122, 16, v47
	v_and_b32_e32 v123, 0xffff0000, v47
	s_waitcnt lgkmcnt(2)
	v_pk_fma_f32 v[116:117], v[84:85], v[36:37], v[116:117]
	v_pk_fma_f32 v[118:119], v[86:87], v[38:39], v[118:119]
	v_pk_fma_f32 v[120:121], v[88:89], v[40:41], v[120:121]
	v_pk_fma_f32 v[122:123], v[90:91], v[42:43], v[122:123]
	v_cvt_pk_bf16_f32 v132, v116, v117
	v_cvt_pk_bf16_f32 v133, v118, v119
	v_cvt_pk_bf16_f32 v134, v120, v121
	v_cvt_pk_bf16_f32 v135, v122, v123
	global_store_dwordx4 v[26:27], v[132:135], off
	ds_read_b128 v[84:87], v8 offset:4352
	ds_read_b128 v[88:91], v8 offset:4368
	s_waitcnt vmcnt(7)
	v_lshlrev_b32_e32 v124, 16, v48
	v_and_b32_e32 v125, 0xffff0000, v48
	v_lshlrev_b32_e32 v126, 16, v49
	v_and_b32_e32 v127, 0xffff0000, v49
	v_lshlrev_b32_e32 v128, 16, v50
	v_and_b32_e32 v129, 0xffff0000, v50
	v_lshlrev_b32_e32 v130, 16, v51
	v_and_b32_e32 v131, 0xffff0000, v51
	s_waitcnt lgkmcnt(2)
	v_pk_fma_f32 v[124:125], v[92:93], v[36:37], v[124:125]
	v_pk_fma_f32 v[126:127], v[94:95], v[38:39], v[126:127]
	v_pk_fma_f32 v[128:129], v[96:97], v[40:41], v[128:129]
	v_pk_fma_f32 v[130:131], v[98:99], v[42:43], v[130:131]
	v_cvt_pk_bf16_f32 v136, v124, v125
	v_cvt_pk_bf16_f32 v137, v126, v127
	v_cvt_pk_bf16_f32 v138, v128, v129
	v_cvt_pk_bf16_f32 v139, v130, v131
	global_store_dwordx4 v[102:103], v[136:139], off
	ds_read_b128 v[92:95], v8 offset:6528
	ds_read_b128 v[96:99], v8 offset:6544
	s_waitcnt vmcnt(7)
	v_lshlrev_b32_e32 v116, 16, v52
	v_and_b32_e32 v117, 0xffff0000, v52
	v_lshlrev_b32_e32 v118, 16, v53
	v_and_b32_e32 v119, 0xffff0000, v53
	v_lshlrev_b32_e32 v120, 16, v54
	v_and_b32_e32 v121, 0xffff0000, v54
	v_lshlrev_b32_e32 v122, 16, v55
	v_and_b32_e32 v123, 0xffff0000, v55
	s_waitcnt lgkmcnt(2)
	v_pk_fma_f32 v[116:117], v[84:85], v[36:37], v[116:117]
	v_pk_fma_f32 v[118:119], v[86:87], v[38:39], v[118:119]
	v_pk_fma_f32 v[120:121], v[88:89], v[40:41], v[120:121]
	v_pk_fma_f32 v[122:123], v[90:91], v[42:43], v[122:123]
	v_cvt_pk_bf16_f32 v132, v116, v117
	v_cvt_pk_bf16_f32 v133, v118, v119
	v_cvt_pk_bf16_f32 v134, v120, v121
	v_cvt_pk_bf16_f32 v135, v122, v123
	global_store_dwordx4 v[104:105], v[132:135], off
	ds_read_b128 v[84:87], v8 offset:8704
	ds_read_b128 v[88:91], v8 offset:8720
	s_waitcnt vmcnt(7)
	v_lshlrev_b32_e32 v124, 16, v56
	v_and_b32_e32 v125, 0xffff0000, v56
	v_lshlrev_b32_e32 v126, 16, v57
	v_and_b32_e32 v127, 0xffff0000, v57
	v_lshlrev_b32_e32 v128, 16, v58
	v_and_b32_e32 v129, 0xffff0000, v58
	v_lshlrev_b32_e32 v130, 16, v59
	v_and_b32_e32 v131, 0xffff0000, v59
	s_waitcnt lgkmcnt(2)
	v_pk_fma_f32 v[124:125], v[92:93], v[36:37], v[124:125]
	v_pk_fma_f32 v[126:127], v[94:95], v[38:39], v[126:127]
	v_pk_fma_f32 v[128:129], v[96:97], v[40:41], v[128:129]
	v_pk_fma_f32 v[130:131], v[98:99], v[42:43], v[130:131]
	v_cvt_pk_bf16_f32 v136, v124, v125
	v_cvt_pk_bf16_f32 v137, v126, v127
	v_cvt_pk_bf16_f32 v138, v128, v129
	v_cvt_pk_bf16_f32 v139, v130, v131
	global_store_dwordx4 v[106:107], v[136:139], off
	ds_read_b128 v[92:95], v8 offset:10880
	ds_read_b128 v[96:99], v8 offset:10896
	s_waitcnt vmcnt(7)
	v_lshlrev_b32_e32 v116, 16, v60
	v_and_b32_e32 v117, 0xffff0000, v60
	v_lshlrev_b32_e32 v118, 16, v61
	v_and_b32_e32 v119, 0xffff0000, v61
	v_lshlrev_b32_e32 v120, 16, v62
	v_and_b32_e32 v121, 0xffff0000, v62
	v_lshlrev_b32_e32 v122, 16, v63
	v_and_b32_e32 v123, 0xffff0000, v63
	s_waitcnt lgkmcnt(2)
	v_pk_fma_f32 v[116:117], v[84:85], v[36:37], v[116:117]
	v_pk_fma_f32 v[118:119], v[86:87], v[38:39], v[118:119]
	v_pk_fma_f32 v[120:121], v[88:89], v[40:41], v[120:121]
	v_pk_fma_f32 v[122:123], v[90:91], v[42:43], v[122:123]
	v_cvt_pk_bf16_f32 v132, v116, v117
	v_cvt_pk_bf16_f32 v133, v118, v119
	v_cvt_pk_bf16_f32 v134, v120, v121
	v_cvt_pk_bf16_f32 v135, v122, v123
	global_store_dwordx4 v[108:109], v[132:135], off
	ds_read_b128 v[84:87], v8 offset:13056
	ds_read_b128 v[88:91], v8 offset:13072
	s_waitcnt vmcnt(7)
	v_lshlrev_b32_e32 v124, 16, v64
	v_and_b32_e32 v125, 0xffff0000, v64
	v_lshlrev_b32_e32 v126, 16, v65
	v_and_b32_e32 v127, 0xffff0000, v65
	v_lshlrev_b32_e32 v128, 16, v66
	v_and_b32_e32 v129, 0xffff0000, v66
	v_lshlrev_b32_e32 v130, 16, v67
	v_and_b32_e32 v131, 0xffff0000, v67
	s_waitcnt lgkmcnt(2)
	v_pk_fma_f32 v[124:125], v[92:93], v[36:37], v[124:125]
	v_pk_fma_f32 v[126:127], v[94:95], v[38:39], v[126:127]
	v_pk_fma_f32 v[128:129], v[96:97], v[40:41], v[128:129]
	v_pk_fma_f32 v[130:131], v[98:99], v[42:43], v[130:131]
	v_cvt_pk_bf16_f32 v136, v124, v125
	v_cvt_pk_bf16_f32 v137, v126, v127
	v_cvt_pk_bf16_f32 v138, v128, v129
	v_cvt_pk_bf16_f32 v139, v130, v131
	global_store_dwordx4 v[110:111], v[136:139], off
	ds_read_b128 v[92:95], v8 offset:15232
	ds_read_b128 v[96:99], v8 offset:15248
	s_waitcnt vmcnt(7)
	v_lshlrev_b32_e32 v116, 16, v68
	v_and_b32_e32 v117, 0xffff0000, v68
	v_lshlrev_b32_e32 v118, 16, v69
	v_and_b32_e32 v119, 0xffff0000, v69
	v_lshlrev_b32_e32 v120, 16, v70
	v_and_b32_e32 v121, 0xffff0000, v70
	v_lshlrev_b32_e32 v122, 16, v71
	v_and_b32_e32 v123, 0xffff0000, v71
	s_waitcnt lgkmcnt(2)
	v_pk_fma_f32 v[116:117], v[84:85], v[36:37], v[116:117]
	v_pk_fma_f32 v[118:119], v[86:87], v[38:39], v[118:119]
	v_pk_fma_f32 v[120:121], v[88:89], v[40:41], v[120:121]
	v_pk_fma_f32 v[122:123], v[90:91], v[42:43], v[122:123]
	v_cvt_pk_bf16_f32 v132, v116, v117
	v_cvt_pk_bf16_f32 v133, v118, v119
	v_cvt_pk_bf16_f32 v134, v120, v121
	v_cvt_pk_bf16_f32 v135, v122, v123
	global_store_dwordx4 v[112:113], v[132:135], off
	s_waitcnt vmcnt(7)
	v_lshlrev_b32_e32 v124, 16, v72
	v_and_b32_e32 v125, 0xffff0000, v72
	v_lshlrev_b32_e32 v126, 16, v73
	v_and_b32_e32 v127, 0xffff0000, v73
	v_lshlrev_b32_e32 v128, 16, v74
	v_and_b32_e32 v129, 0xffff0000, v74
	v_lshlrev_b32_e32 v130, 16, v75
	v_and_b32_e32 v131, 0xffff0000, v75
	s_waitcnt lgkmcnt(0)
	v_pk_fma_f32 v[124:125], v[92:93], v[36:37], v[124:125]
	v_pk_fma_f32 v[126:127], v[94:95], v[38:39], v[126:127]
	v_pk_fma_f32 v[128:129], v[96:97], v[40:41], v[128:129]
	v_pk_fma_f32 v[130:131], v[98:99], v[42:43], v[130:131]
	v_cvt_pk_bf16_f32 v136, v124, v125
	v_cvt_pk_bf16_f32 v137, v126, v127
	v_cvt_pk_bf16_f32 v138, v128, v129
	v_cvt_pk_bf16_f32 v139, v130, v131
	global_store_dwordx4 v[114:115], v[136:139], off

.LBB0_285:
	s_andn2_b64 vcc, exec, s[22:23]
	s_cbranch_vccnz .LBB0_372
	v_readlane_b32 s22, v254, 44
	v_readlane_b32 s23, v254, 45
	s_andn2_b64 vcc, exec, s[22:23]
	s_cbranch_vccnz .LBB0_372
	v_mov_b32_e32 v10, v202
	v_readlane_b32 s8, v254, 48
	v_bfe_u32 v135, v10, 4, 2
	v_bitop3_b32 v0, v135, v10, 3 bitop3:0x78
	v_bfe_u32 v4, v10, 2, 4
	v_lshlrev_b32_e32 v0, 4, v0
	v_ashrrev_i32_e32 v136, 6, v10
	v_or_b32_e32 v11, s8, v4
	v_lshl_add_u64 v[2:3], s[20:21], 0, v[0:1]
	v_readlane_b32 s8, v254, 46
	v_readlane_b32 s20, v254, 49
	v_readlane_b32 s21, v254, 50
	v_or_b32_e32 v12, s8, v4
	v_cmp_gt_i32_e32 vcc, 16, v136
	v_lshl_add_u64 v[4:5], s[20:21], 0, v[0:1]
	v_lshlrev_b32_e32 v0, 4, v136
	v_cndmask_b32_e32 v8, v11, v12, vcc
	v_add_u32_e32 v8, v8, v0
	v_ashrrev_i32_e32 v9, 31, v8
	v_cndmask_b32_e32 v7, v3, v5, vcc
	v_cndmask_b32_e32 v6, v2, v4, vcc
	v_lshlrev_b64 v[8:9], 11, v[8:9]
	v_cmp_gt_i32_e32 vcc, 8, v136
	v_lshl_add_u64 v[126:127], v[6:7], 0, v[8:9]
	s_movk_i32 s8, 0x80
	v_cndmask_b32_e32 v8, v11, v12, vcc
	v_add3_u32 v8, v0, v8, s8
	v_ashrrev_i32_e32 v9, 31, v8
	v_cndmask_b32_e32 v7, v3, v5, vcc
	v_cndmask_b32_e32 v6, v2, v4, vcc
	v_lshlrev_b64 v[8:9], 11, v[8:9]
	v_cmp_gt_i32_e32 vcc, 0, v136
	v_and_b32_e32 v134, 63, v10
	v_lshl_add_u64 v[128:129], v[6:7], 0, v[8:9]
	v_cndmask_b32_e32 v6, v11, v12, vcc
	s_movk_i32 s8, 0x100
	v_cndmask_b32_e32 v2, v2, v4, vcc
	v_add3_u32 v4, v0, v6, s8
	v_lshlrev_b32_e32 v0, 4, v134
	v_lshl_or_b32 v137, v136, 10, v0
	v_add_u32_e32 v0, 0x2000, v137
	v_readfirstlane_b32 s8, v137
	v_cndmask_b32_e32 v3, v3, v5, vcc
	v_ashrrev_i32_e32 v5, 31, v4
	s_mov_b32 m0, s8
	v_readfirstlane_b32 s8, v0
	v_add_u32_e32 v0, 0x4000, v137
	v_lshlrev_b64 v[4:5], 11, v[4:5]
	s_barrier
	global_load_lds_dwordx4 v[126:127], off
	s_mov_b32 m0, s8
	v_readfirstlane_b32 s8, v0
	v_add_u32_e32 v0, 0x6000, v137
	v_lshl_add_u64 v[130:131], v[2:3], 0, v[4:5]
	global_load_lds_dwordx4 v[128:129], off
	s_mov_b32 m0, s8
	v_readfirstlane_b32 s8, v0
	v_add_u32_e32 v0, 0x8000, v137
	global_load_lds_dwordx4 v[130:131], off
	v_lshl_add_u64 v[2:3], v[126:127], 0, 64
	s_mov_b32 m0, s8
	v_readfirstlane_b32 s8, v0
	v_add_u32_e32 v0, 0xa000, v137
	global_load_lds_dwordx4 v[2:3], off
	v_lshl_add_u64 v[2:3], v[128:129], 0, 64
	s_mov_b32 m0, s8
	v_readfirstlane_b32 s8, v0
	v_add_u32_e32 v0, 0xc000, v137
	global_load_lds_dwordx4 v[2:3], off
	v_lshl_add_u64 v[2:3], v[130:131], 0, 64
	s_mov_b32 m0, s8
	v_readfirstlane_b32 s8, v0
	v_add_u32_e32 v0, 0xe000, v137
	global_load_lds_dwordx4 v[2:3], off
	v_lshl_add_u64 v[2:3], v[126:127], 0, s[10:11]
	s_mov_b32 m0, s8
	v_readfirstlane_b32 s8, v0
	v_add_u32_e32 v0, 0x10000, v137
	global_load_lds_dwordx4 v[2:3], off
	v_lshl_add_u64 v[2:3], v[128:129], 0, s[10:11]
	s_mov_b32 m0, s8
	v_readfirstlane_b32 s8, v0
	global_load_lds_dwordx4 v[2:3], off
	v_lshl_add_u64 v[2:3], v[130:131], 0, s[10:11]
	s_mov_b32 m0, s8
	v_and_b32_e32 v138, 15, v10
	global_load_lds_dwordx4 v[2:3], off
	v_readfirstlane_b32 s44, v126
	v_readfirstlane_b32 s45, v127
	v_readfirstlane_b32 s30, v130
	v_readfirstlane_b32 s31, v131
	v_readfirstlane_b32 s29, v137
	s_nop 1
	v_subrev_u32_e32 v126, s44, v126
	v_subrev_u32_e32 v128, s44, v128
	v_subrev_u32_e32 v130, s30, v130
	s_add_u32 s44, s44, 0xc0
	s_addc_u32 s45, s45, 0
	s_add_u32 s30, s30, 0xc0
	s_addc_u32 s31, s31, 0
	v_bfe_u32 v2, v10, 2, 2
	v_and_b32_e32 v139, 1, v136
	v_xor_b32_e32 v2, v135, v2
	v_lshlrev_b32_e32 v3, 6, v138
	v_ashrrev_i32_e32 v0, 7, v10
	v_lshl_or_b32 v2, v2, 4, v3
	v_lshlrev_b32_e32 v3, 12, v139
	s_movk_i32 s8, 0x4000
	s_waitcnt vmcnt(9)
	v_mov_b32_e32 v19, 0
	v_mov_b32_e32 v20, 0
	v_mov_b32_e32 v21, 0
	v_mov_b32_e32 v30, 0
	v_mov_b32_e32 v31, 0
	v_mov_b32_e32 v32, 0
	v_mov_b32_e32 v33, 0
	v_mov_b32_e32 v35, 0
	v_mov_b32_e32 v36, 0
	v_mov_b32_e32 v37, 0
	v_mov_b32_e32 v38, 0
	v_mov_b32_e32 v39, 0
	v_mov_b32_e32 v40, 0
	v_mov_b32_e32 v41, 0
	v_mov_b32_e32 v42, 0
	v_mov_b32_e32 v43, 0
	v_mov_b32_e32 v44, 0
	v_mov_b32_e32 v45, 0
	v_mov_b32_e32 v46, 0
	v_mov_b32_e32 v47, 0
	v_mov_b32_e32 v48, 0
	v_mov_b32_e32 v49, 0
	v_mov_b32_e32 v50, 0
	v_mov_b32_e32 v51, 0
	v_mov_b32_e32 v52, 0
	v_mov_b32_e32 v53, 0
	v_mov_b32_e32 v54, 0
	v_mov_b32_e32 v55, 0
	v_mov_b32_e32 v56, 0
	v_mov_b32_e32 v57, 0
	v_mov_b32_e32 v58, 0
	v_mov_b32_e32 v59, 0
	v_mov_b32_e32 v60, 0
	v_mov_b32_e32 v61, 0
	v_mov_b32_e32 v62, 0
	v_mov_b32_e32 v63, 0
	v_mov_b32_e32 v64, 0
	v_mov_b32_e32 v65, 0
	v_mov_b32_e32 v66, 0
	v_mov_b32_e32 v67, 0
	v_mov_b32_e32 v68, 0
	v_mov_b32_e32 v69, 0
	v_mov_b32_e32 v70, 0
	v_mov_b32_e32 v71, 0
	v_mov_b32_e32 v72, 0
	v_mov_b32_e32 v73, 0
	v_mov_b32_e32 v74, 0
	v_mov_b32_e32 v75, 0
	v_mov_b32_e32 v76, 0
	v_mov_b32_e32 v77, 0
	v_mov_b32_e32 v78, 0
	v_mov_b32_e32 v79, 0
	v_mov_b32_e32 v80, 0
	v_mov_b32_e32 v81, 0
	v_mov_b32_e32 v82, 0
	v_mov_b32_e32 v83, 0
	v_mov_b32_e32 v84, 0
	v_mov_b32_e32 v85, 0
	v_mov_b32_e32 v86, 0
	v_mov_b32_e32 v87, 0
	v_mov_b32_e32 v88, 0
	v_mov_b32_e32 v89, 0
	v_mov_b32_e32 v90, 0
	v_mov_b32_e32 v91, 0
	v_mov_b32_e32 v92, 0
	v_mov_b32_e32 v93, 0
	v_mov_b32_e32 v94, 0
	v_mov_b32_e32 v95, 0
	v_mov_b32_e32 v96, 0
	v_mov_b32_e32 v97, 0
	v_mov_b32_e32 v98, 0
	v_mov_b32_e32 v99, 0
	v_mov_b32_e32 v100, 0
	v_mov_b32_e32 v101, 0
	v_mov_b32_e32 v102, 0
	v_mov_b32_e32 v103, 0
	v_mov_b32_e32 v104, 0
	v_mov_b32_e32 v105, 0
	s_waitcnt vmcnt(6)
	v_lshl_or_b32 v140, v0, 12, v2
	v_or3_b32 v141, v3, v2, s8
	s_waitcnt lgkmcnt(0)
	s_barrier
	ds_read_b128 v[2:5], v140
	ds_read_b128 v[6:9], v140 offset:1024
	ds_read_b128 v[10:13], v140 offset:2048
	ds_read_b128 v[14:17], v140 offset:3072
	ds_read_b128 v[26:29], v141
	ds_read_b128 v[22:25], v141 offset:1024
	v_cmp_lt_i32_e32 vcc, 3, v136
	s_and_saveexec_b64 s[20:21], vcc
	s_cbranch_execz .LBB0_289
.LBB0_289:
	s_or_b64 exec, exec, s[20:21]
	v_mov_b32_e32 v18, 0
	v_mov_b32_e32 v34, 0
	v_add_u32_e32 v142, 0x800, v141
	s_mov_b64 s[20:21], 0
	s_mov_b32 s8, 3
	s_branch .LBB0_291

.LBB0_305:
	v_cmp_gt_i32_e32 vcc, 4, v136
	s_and_saveexec_b64 s[20:21], vcc
	s_cbranch_execz .LBB0_307
.LBB0_307:
	s_or_b64 exec, exec, s[20:21]
	s_add_i32 s8, s16, 6
	s_cmp_gt_u32 s8, 14
	s_movk_i32 s8, 0x4400
	v_mul_lo_u32 v42, v136, s8
	v_lshl_or_b32 v3, v138, 2, v42
	s_movk_i32 s8, 0x440
	v_mad_u32_u24 v3, v135, s8, v3
	v_add_u32_e32 v4, 0x1000, v3
	v_add_u32_e32 v5, 0x1400, v3
	s_waitcnt vmcnt(0) lgkmcnt(0)
	s_barrier
	ds_write2_b32 v3, v102, v90 offset1:16
	ds_write2_b32 v3, v103, v91 offset0:68 offset1:84
	ds_write2_b32 v3, v104, v92 offset0:136 offset1:152
	ds_write2_b32 v3, v105, v93 offset0:204 offset1:220
	ds_write2_b32 v3, v74, v94 offset0:32 offset1:48
	ds_write2_b32 v3, v75, v95 offset0:100 offset1:116
	ds_write2_b32 v3, v76, v96 offset0:168 offset1:184
	ds_write2_b32 v3, v77, v97 offset0:236 offset1:252
	ds_write2_b32 v4, v98, v78 offset0:64 offset1:80
	ds_write2_b32 v4, v99, v79 offset0:132 offset1:148
	ds_write2_b32 v4, v100, v80 offset0:200 offset1:216
	ds_write2_b32 v5, v101, v81 offset0:12 offset1:28
	ds_write2_b32 v4, v58, v82 offset0:96 offset1:112
	ds_write2_b32 v4, v59, v83 offset0:164 offset1:180
	ds_write2_b32 v4, v60, v84 offset0:232 offset1:248
	ds_write2_b32 v5, v61, v85 offset0:44 offset1:60
	v_add_u32_e32 v4, 0x2000, v3
	v_add_u32_e32 v5, 0x2400, v3
	ds_write2_b32 v4, v86, v62 offset0:128 offset1:144
	ds_write2_b32 v4, v87, v63 offset0:196 offset1:212
	ds_write2_b32 v5, v88, v64 offset0:8 offset1:24
	ds_write2_b32 v5, v89, v65 offset0:76 offset1:92
	ds_write2_b32 v4, v38, v66 offset0:160 offset1:176
	ds_write2_b32 v4, v39, v67 offset0:228 offset1:244
	ds_write2_b32 v5, v40, v68 offset0:40 offset1:56
	ds_write2_b32 v5, v41, v69 offset0:108 offset1:124
	v_add_u32_e32 v4, 0x3000, v3
	v_add_u32_e32 v3, 0x3400, v3
	v_readlane_b32 s8, v254, 46
	ds_write2_b32 v4, v70, v46 offset0:192 offset1:208
	ds_write2_b32 v3, v71, v47 offset0:4 offset1:20
	ds_write2_b32 v3, v72, v48 offset0:72 offset1:88
	ds_write2_b32 v3, v73, v49 offset0:140 offset1:156
	ds_write2_b32 v4, v30, v34 offset0:224 offset1:240
	ds_write2_b32 v3, v31, v35 offset0:36 offset1:52
	ds_write2_b32 v3, v32, v36 offset0:104 offset1:120
	ds_write2_b32 v3, v33, v37 offset0:172 offset1:188
	v_lshl_add_u32 v34, v0, 6, s8
	v_lshrrev_b32_e32 v35, 3, v134
	v_lshlrev_b32_e32 v0, 3, v134
	v_or_b32_e32 v28, v34, v35
	v_lshlrev_b32_e32 v2, 6, v139
	v_and_b32_e32 v0, 56, v0
	v_readlane_b32 s8, v254, 47
	v_add_u32_e32 v30, 0xfffff000, v28
	v_cmp_lt_i32_e64 s[40:41], s1, v28
	v_or3_b32 v18, v2, s8, v0
	v_lshrrev_b32_e32 v2, 10, v30
	v_cndmask_b32_e64 v2, 4, v2, s[40:41]
	s_mul_i32 s8, s18, 5
	v_add_u32_e32 v4, s8, v2
	s_cselect_b64 s[20:21], -1, 0
	v_mov_b64_e32 v[2:3], s[14:15]
	v_mad_i64_i32 v[2:3], s[22:23], v4, s82, v[2:3]
	v_lshlrev_b32_e32 v26, 2, v18
	v_mov_b32_e32 v27, v1
	v_lshl_add_u64 v[10:11], v[2:3], 0, v[26:27]
	s_mov_b64 s[22:23], 0x8602000
	v_lshl_add_u64 v[10:11], v[10:11], 0, s[22:23]
	global_load_dwordx4 v[108:111], v[10:11], off
	global_load_dwordx4 v[112:115], v[10:11], off offset:16
	v_mul_u32_u24_e32 v37, 0x110, v35
	v_lshlrev_b32_e32 v36, 2, v0
	v_add3_u32 v8, v42, v37, v36
	v_lshlrev_b32_e32 v0, 1, v18
	v_mov_b32_e32 v10, v28
	v_ashrrev_i32_e32 v11, 31, v10
	v_lshlrev_b64 v[10:11], 11, v[10:11]
	v_lshl_add_u64 v[10:11], s[66:67], 0, v[10:11]
	v_lshl_add_u64 v[116:117], v[10:11], 0, v[0:1]
	v_or3_b32 v10, v35, v34, 8
	v_ashrrev_i32_e32 v11, 31, v10
	v_lshlrev_b64 v[10:11], 11, v[10:11]
	v_lshl_add_u64 v[10:11], s[66:67], 0, v[10:11]
	v_lshl_add_u64 v[118:119], v[10:11], 0, v[0:1]
	v_or3_b32 v10, v35, v34, 16
	v_ashrrev_i32_e32 v11, 31, v10
	v_lshlrev_b64 v[10:11], 11, v[10:11]
	v_lshl_add_u64 v[10:11], s[66:67], 0, v[10:11]
	v_lshl_add_u64 v[120:121], v[10:11], 0, v[0:1]
	v_or3_b32 v10, v35, v34, 24
	v_ashrrev_i32_e32 v11, 31, v10
	v_lshlrev_b64 v[10:11], 11, v[10:11]
	v_lshl_add_u64 v[10:11], s[66:67], 0, v[10:11]
	v_lshl_add_u64 v[122:123], v[10:11], 0, v[0:1]
	v_or3_b32 v10, v35, v34, 32
	v_ashrrev_i32_e32 v11, 31, v10
	v_lshlrev_b64 v[10:11], 11, v[10:11]
	v_lshl_add_u64 v[10:11], s[66:67], 0, v[10:11]
	v_lshl_add_u64 v[124:125], v[10:11], 0, v[0:1]
	v_or3_b32 v10, v35, v34, 40
	v_ashrrev_i32_e32 v11, 31, v10
	v_lshlrev_b64 v[10:11], 11, v[10:11]
	v_lshl_add_u64 v[10:11], s[66:67], 0, v[10:11]
	v_lshl_add_u64 v[126:127], v[10:11], 0, v[0:1]
	v_or3_b32 v10, v35, v34, 48
	v_ashrrev_i32_e32 v11, 31, v10
	v_lshlrev_b64 v[10:11], 11, v[10:11]
	v_lshl_add_u64 v[10:11], s[66:67], 0, v[10:11]
	v_lshl_add_u64 v[128:129], v[10:11], 0, v[0:1]
	v_or3_b32 v10, v35, v34, 56
	v_ashrrev_i32_e32 v11, 31, v10
	v_lshlrev_b64 v[10:11], 11, v[10:11]
	v_lshl_add_u64 v[10:11], s[66:67], 0, v[10:11]
	v_lshl_add_u64 v[130:131], v[10:11], 0, v[0:1]
	s_and_b64 vcc, exec, s[20:21]
	s_cbranch_vccz .Lg3_from_input
	global_load_dwordx4 v[44:47], v[116:117], off
	global_load_dwordx4 v[48:51], v[118:119], off
	global_load_dwordx4 v[52:55], v[120:121], off
	global_load_dwordx4 v[56:59], v[122:123], off
	global_load_dwordx4 v[60:63], v[124:125], off
	global_load_dwordx4 v[64:67], v[126:127], off
	global_load_dwordx4 v[68:71], v[128:129], off
	global_load_dwordx4 v[72:75], v[130:131], off
	ds_read_b128 v[132:135], v8
	ds_read_b128 v[136:139], v8 offset:16
	ds_read_b128 v[140:143], v8 offset:2176
	ds_read_b128 v[144:147], v8 offset:2192
	s_waitcnt vmcnt(7)
	v_lshlrev_b32_e32 v148, 16, v44
	v_and_b32_e32 v149, 0xffff0000, v44
	v_lshlrev_b32_e32 v150, 16, v45
	v_and_b32_e32 v151, 0xffff0000, v45
	v_lshlrev_b32_e32 v152, 16, v46
	v_and_b32_e32 v153, 0xffff0000, v46
	v_lshlrev_b32_e32 v154, 16, v47
	v_and_b32_e32 v155, 0xffff0000, v47
	s_waitcnt lgkmcnt(2)
	v_pk_fma_f32 v[148:149], v[132:133], v[108:109], v[148:149]
	v_pk_fma_f32 v[150:151], v[134:135], v[110:111], v[150:151]
	v_pk_fma_f32 v[152:153], v[136:137], v[112:113], v[152:153]
	v_pk_fma_f32 v[154:155], v[138:139], v[114:115], v[154:155]
	v_cvt_pk_bf16_f32 v164, v148, v149
	v_cvt_pk_bf16_f32 v165, v150, v151
	v_cvt_pk_bf16_f32 v166, v152, v153
	v_cvt_pk_bf16_f32 v167, v154, v155
	global_store_dwordx4 v[116:117], v[164:167], off
	ds_read_b128 v[132:135], v8 offset:4352
	ds_read_b128 v[136:139], v8 offset:4368
	s_waitcnt vmcnt(7)
	v_lshlrev_b32_e32 v156, 16, v48
	v_and_b32_e32 v157, 0xffff0000, v48
	v_lshlrev_b32_e32 v158, 16, v49
	v_and_b32_e32 v159, 0xffff0000, v49
	v_lshlrev_b32_e32 v160, 16, v50
	v_and_b32_e32 v161, 0xffff0000, v50
	v_lshlrev_b32_e32 v162, 16, v51
	v_and_b32_e32 v163, 0xffff0000, v51
	s_waitcnt lgkmcnt(2)
	v_pk_fma_f32 v[156:157], v[140:141], v[108:109], v[156:157]
	v_pk_fma_f32 v[158:159], v[142:143], v[110:111], v[158:159]
	v_pk_fma_f32 v[160:161], v[144:145], v[112:113], v[160:161]
	v_pk_fma_f32 v[162:163], v[146:147], v[114:115], v[162:163]
	v_cvt_pk_bf16_f32 v168, v156, v157
	v_cvt_pk_bf16_f32 v169, v158, v159
	v_cvt_pk_bf16_f32 v170, v160, v161
	v_cvt_pk_bf16_f32 v171, v162, v163
	global_store_dwordx4 v[118:119], v[168:171], off
	ds_read_b128 v[140:143], v8 offset:6528
	ds_read_b128 v[144:147], v8 offset:6544
	s_waitcnt vmcnt(7)
	v_lshlrev_b32_e32 v148, 16, v52
	v_and_b32_e32 v149, 0xffff0000, v52
	v_lshlrev_b32_e32 v150, 16, v53
	v_and_b32_e32 v151, 0xffff0000, v53
	v_lshlrev_b32_e32 v152, 16, v54
	v_and_b32_e32 v153, 0xffff0000, v54
	v_lshlrev_b32_e32 v154, 16, v55
	v_and_b32_e32 v155, 0xffff0000, v55
	s_waitcnt lgkmcnt(2)
	v_pk_fma_f32 v[148:149], v[132:133], v[108:109], v[148:149]
	v_pk_fma_f32 v[150:151], v[134:135], v[110:111], v[150:151]
	v_pk_fma_f32 v[152:153], v[136:137], v[112:113], v[152:153]
	v_pk_fma_f32 v[154:155], v[138:139], v[114:115], v[154:155]
	v_cvt_pk_bf16_f32 v164, v148, v149
	v_cvt_pk_bf16_f32 v165, v150, v151
	v_cvt_pk_bf16_f32 v166, v152, v153
	v_cvt_pk_bf16_f32 v167, v154, v155
	global_store_dwordx4 v[120:121], v[164:167], off
	ds_read_b128 v[132:135], v8 offset:8704
	ds_read_b128 v[136:139], v8 offset:8720
	s_waitcnt vmcnt(7)
	v_lshlrev_b32_e32 v156, 16, v56
	v_and_b32_e32 v157, 0xffff0000, v56
	v_lshlrev_b32_e32 v158, 16, v57
	v_and_b32_e32 v159, 0xffff0000, v57
	v_lshlrev_b32_e32 v160, 16, v58
	v_and_b32_e32 v161, 0xffff0000, v58
	v_lshlrev_b32_e32 v162, 16, v59
	v_and_b32_e32 v163, 0xffff0000, v59
	s_waitcnt lgkmcnt(2)
	v_pk_fma_f32 v[156:157], v[140:141], v[108:109], v[156:157]
	v_pk_fma_f32 v[158:159], v[142:143], v[110:111], v[158:159]
	v_pk_fma_f32 v[160:161], v[144:145], v[112:113], v[160:161]
	v_pk_fma_f32 v[162:163], v[146:147], v[114:115], v[162:163]
	v_cvt_pk_bf16_f32 v168, v156, v157
	v_cvt_pk_bf16_f32 v169, v158, v159
	v_cvt_pk_bf16_f32 v170, v160, v161
	v_cvt_pk_bf16_f32 v171, v162, v163
	global_store_dwordx4 v[122:123], v[168:171], off
	ds_read_b128 v[140:143], v8 offset:10880
	ds_read_b128 v[144:147], v8 offset:10896
	s_waitcnt vmcnt(7)
	v_lshlrev_b32_e32 v148, 16, v60
	v_and_b32_e32 v149, 0xffff0000, v60
	v_lshlrev_b32_e32 v150, 16, v61
	v_and_b32_e32 v151, 0xffff0000, v61
	v_lshlrev_b32_e32 v152, 16, v62
	v_and_b32_e32 v153, 0xffff0000, v62
	v_lshlrev_b32_e32 v154, 16, v63
	v_and_b32_e32 v155, 0xffff0000, v63
	s_waitcnt lgkmcnt(2)
	v_pk_fma_f32 v[148:149], v[132:133], v[108:109], v[148:149]
	v_pk_fma_f32 v[150:151], v[134:135], v[110:111], v[150:151]
	v_pk_fma_f32 v[152:153], v[136:137], v[112:113], v[152:153]
	v_pk_fma_f32 v[154:155], v[138:139], v[114:115], v[154:155]
	v_cvt_pk_bf16_f32 v164, v148, v149
	v_cvt_pk_bf16_f32 v165, v150, v151
	v_cvt_pk_bf16_f32 v166, v152, v153
	v_cvt_pk_bf16_f32 v167, v154, v155
	global_store_dwordx4 v[124:125], v[164:167], off
	ds_read_b128 v[132:135], v8 offset:13056
	ds_read_b128 v[136:139], v8 offset:13072
	s_waitcnt vmcnt(7)
	v_lshlrev_b32_e32 v156, 16, v64
	v_and_b32_e32 v157, 0xffff0000, v64
	v_lshlrev_b32_e32 v158, 16, v65
	v_and_b32_e32 v159, 0xffff0000, v65
	v_lshlrev_b32_e32 v160, 16, v66
	v_and_b32_e32 v161, 0xffff0000, v66
	v_lshlrev_b32_e32 v162, 16, v67
	v_and_b32_e32 v163, 0xffff0000, v67
	s_waitcnt lgkmcnt(2)
	v_pk_fma_f32 v[156:157], v[140:141], v[108:109], v[156:157]
	v_pk_fma_f32 v[158:159], v[142:143], v[110:111], v[158:159]
	v_pk_fma_f32 v[160:161], v[144:145], v[112:113], v[160:161]
	v_pk_fma_f32 v[162:163], v[146:147], v[114:115], v[162:163]
	v_cvt_pk_bf16_f32 v168, v156, v157
	v_cvt_pk_bf16_f32 v169, v158, v159
	v_cvt_pk_bf16_f32 v170, v160, v161
	v_cvt_pk_bf16_f32 v171, v162, v163
	global_store_dwordx4 v[126:127], v[168:171], off
	ds_read_b128 v[140:143], v8 offset:15232
	ds_read_b128 v[144:147], v8 offset:15248
	s_waitcnt vmcnt(7)
	v_lshlrev_b32_e32 v148, 16, v68
	v_and_b32_e32 v149, 0xffff0000, v68
	v_lshlrev_b32_e32 v150, 16, v69
	v_and_b32_e32 v151, 0xffff0000, v69
	v_lshlrev_b32_e32 v152, 16, v70
	v_and_b32_e32 v153, 0xffff0000, v70
	v_lshlrev_b32_e32 v154, 16, v71
	v_and_b32_e32 v155, 0xffff0000, v71
	s_waitcnt lgkmcnt(2)
	v_pk_fma_f32 v[148:149], v[132:133], v[108:109], v[148:149]
	v_pk_fma_f32 v[150:151], v[134:135], v[110:111], v[150:151]
	v_pk_fma_f32 v[152:153], v[136:137], v[112:113], v[152:153]
	v_pk_fma_f32 v[154:155], v[138:139], v[114:115], v[154:155]
	v_cvt_pk_bf16_f32 v164, v148, v149
	v_cvt_pk_bf16_f32 v165, v150, v151
	v_cvt_pk_bf16_f32 v166, v152, v153
	v_cvt_pk_bf16_f32 v167, v154, v155
	global_store_dwordx4 v[128:129], v[164:167], off
	s_waitcnt vmcnt(7)
	v_lshlrev_b32_e32 v156, 16, v72
	v_and_b32_e32 v157, 0xffff0000, v72
	v_lshlrev_b32_e32 v158, 16, v73
	v_and_b32_e32 v159, 0xffff0000, v73
	v_lshlrev_b32_e32 v160, 16, v74
	v_and_b32_e32 v161, 0xffff0000, v74
	v_lshlrev_b32_e32 v162, 16, v75
	v_and_b32_e32 v163, 0xffff0000, v75
	s_waitcnt lgkmcnt(0)
	v_pk_fma_f32 v[156:157], v[140:141], v[108:109], v[156:157]
	v_pk_fma_f32 v[158:159], v[142:143], v[110:111], v[158:159]
	v_pk_fma_f32 v[160:161], v[144:145], v[112:113], v[160:161]
	v_pk_fma_f32 v[162:163], v[146:147], v[114:115], v[162:163]
	v_cvt_pk_bf16_f32 v168, v156, v157
	v_cvt_pk_bf16_f32 v169, v158, v159
	v_cvt_pk_bf16_f32 v170, v160, v161
	v_cvt_pk_bf16_f32 v171, v162, v163
	global_store_dwordx4 v[130:131], v[168:171], off
	s_branch .LBB0_372

.LBB0_403:
	s_andn2_b64 vcc, exec, s[22:23]
	s_cbranch_vccnz .LBB0_428
	v_readlane_b32 s22, v254, 44
	v_readlane_b32 s23, v254, 45
	s_andn2_b64 vcc, exec, s[22:23]
	s_cbranch_vccnz .LBB0_428
	v_mov_b32_e32 v8, v202
	v_readlane_b32 s8, v254, 48
	v_bfe_u32 v201, v8, 4, 2
	v_bitop3_b32 v0, v201, v8, 3 bitop3:0x78
	v_bfe_u32 v4, v8, 2, 4
	v_lshlrev_b32_e32 v0, 4, v0
	v_ashrrev_i32_e32 v230, 6, v8
	v_or_b32_e32 v9, s8, v4
	v_lshl_add_u64 v[2:3], s[20:21], 0, v[0:1]
	v_readlane_b32 s8, v254, 46
	v_readlane_b32 s20, v254, 55
	v_readlane_b32 s21, v254, 56
	v_or_b32_e32 v10, s8, v4
	v_cmp_gt_i32_e32 vcc, 16, v230
	v_lshl_add_u64 v[4:5], s[20:21], 0, v[0:1]
	v_lshlrev_b32_e32 v0, 4, v230
	v_cndmask_b32_e32 v11, v9, v10, vcc
	v_cndmask_b32_e32 v7, v3, v5, vcc
	v_cndmask_b32_e32 v6, v2, v4, vcc
	v_add_u32_e32 v11, v11, v0
	v_cmp_gt_i32_e32 vcc, 8, v230
	v_mad_i64_i32 v[126:127], s[20:21], v11, s84, v[6:7]
	s_nop 0
	v_cndmask_b32_e32 v11, v9, v10, vcc
	s_movk_i32 s8, 0x80
	v_cndmask_b32_e32 v7, v3, v5, vcc
	v_cndmask_b32_e32 v6, v2, v4, vcc
	v_add3_u32 v11, v0, v11, s8
	v_cmp_gt_i32_e32 vcc, 0, v230
	v_mad_i64_i32 v[128:129], s[20:21], v11, s84, v[6:7]
	s_nop 0
	v_cndmask_b32_e32 v6, v9, v10, vcc
	s_movk_i32 s8, 0x100
	v_and_b32_e32 v200, 63, v8
	v_cndmask_b32_e32 v3, v3, v5, vcc
	v_cndmask_b32_e32 v2, v2, v4, vcc
	v_add3_u32 v0, v0, v6, s8
	v_mad_i64_i32 v[130:131], s[20:21], v0, s84, v[2:3]
	v_lshlrev_b32_e32 v0, 4, v200
	v_lshl_or_b32 v232, v230, 10, v0
	v_add_u32_e32 v0, 0x2000, v232
	v_readfirstlane_b32 s8, v232
	s_mov_b32 m0, s8
	v_readfirstlane_b32 s8, v0
	v_add_u32_e32 v0, 0x4000, v232
	s_barrier
	global_load_lds_dwordx4 v[126:127], off
	s_mov_b32 m0, s8
	v_readfirstlane_b32 s8, v0
	v_add_u32_e32 v0, 0x6000, v232
	global_load_lds_dwordx4 v[128:129], off
	s_mov_b32 m0, s8
	v_readfirstlane_b32 s8, v0
	v_add_u32_e32 v0, 0x8000, v232
	global_load_lds_dwordx4 v[130:131], off
	v_lshl_add_u64 v[2:3], v[126:127], 0, 64
	s_mov_b32 m0, s8
	v_readfirstlane_b32 s8, v0
	v_add_u32_e32 v0, 0xa000, v232
	global_load_lds_dwordx4 v[2:3], off
	v_lshl_add_u64 v[2:3], v[128:129], 0, 64
	s_mov_b32 m0, s8
	v_readfirstlane_b32 s8, v0
	v_add_u32_e32 v0, 0xc000, v232
	global_load_lds_dwordx4 v[2:3], off
	v_lshl_add_u64 v[2:3], v[130:131], 0, 64
	s_mov_b32 m0, s8
	v_readfirstlane_b32 s8, v0
	v_add_u32_e32 v0, 0xe000, v232
	global_load_lds_dwordx4 v[2:3], off
	v_lshl_add_u64 v[2:3], v[126:127], 0, s[10:11]
	s_mov_b32 m0, s8
	v_readfirstlane_b32 s8, v0
	v_add_u32_e32 v0, 0x10000, v232
	global_load_lds_dwordx4 v[2:3], off
	v_lshl_add_u64 v[2:3], v[128:129], 0, s[10:11]
	s_mov_b32 m0, s8
	v_readfirstlane_b32 s8, v0
	global_load_lds_dwordx4 v[2:3], off
	v_lshl_add_u64 v[2:3], v[130:131], 0, s[10:11]
	s_mov_b32 m0, s8
	v_and_b32_e32 v234, 15, v8
	global_load_lds_dwordx4 v[2:3], off
	v_readfirstlane_b32 s90, v126
	v_readfirstlane_b32 s91, v127
	v_readfirstlane_b32 s92, v130
	v_readfirstlane_b32 s93, v131
	v_readfirstlane_b32 s88, v232
	s_nop 1
	v_subrev_u32_e32 v126, s90, v126
	v_subrev_u32_e32 v128, s90, v128
	v_subrev_u32_e32 v130, s92, v130
	s_add_u32 s90, s90, 0xc0
	s_addc_u32 s91, s91, 0
	s_add_u32 s92, s92, 0xc0
	s_addc_u32 s93, s93, 0
	v_bfe_u32 v2, v8, 2, 2
	v_and_b32_e32 v231, 1, v230
	v_xor_b32_e32 v2, v201, v2
	v_lshlrev_b32_e32 v3, 6, v234
	v_ashrrev_i32_e32 v0, 7, v8
	v_lshl_or_b32 v2, v2, 4, v3
	v_lshlrev_b32_e32 v3, 12, v231
	s_movk_i32 s8, 0x4000
	s_waitcnt vmcnt(9)
	v_mov_b32_e32 v31, 0
	v_mov_b32_e32 v32, 0
	v_mov_b32_e32 v33, 0
	v_mov_b32_e32 v38, 0
	v_mov_b32_e32 v39, 0
	v_mov_b32_e32 v40, 0
	v_mov_b32_e32 v41, 0
	v_mov_b32_e32 v43, 0
	v_mov_b32_e32 v44, 0
	v_mov_b32_e32 v45, 0
	v_mov_b32_e32 v46, 0
	v_mov_b32_e32 v47, 0
	v_mov_b32_e32 v48, 0
	v_mov_b32_e32 v49, 0
	v_mov_b32_e32 v50, 0
	v_mov_b32_e32 v51, 0
	v_mov_b32_e32 v52, 0
	v_mov_b32_e32 v53, 0
	v_mov_b32_e32 v54, 0
	v_mov_b32_e32 v55, 0
	v_mov_b32_e32 v56, 0
	v_mov_b32_e32 v57, 0
	v_mov_b32_e32 v58, 0
	v_mov_b32_e32 v59, 0
	v_mov_b32_e32 v60, 0
	v_mov_b32_e32 v61, 0
	v_mov_b32_e32 v62, 0
	v_mov_b32_e32 v63, 0
	v_mov_b32_e32 v64, 0
	v_mov_b32_e32 v65, 0
	v_mov_b32_e32 v66, 0
	v_mov_b32_e32 v67, 0
	v_mov_b32_e32 v68, 0
	v_mov_b32_e32 v69, 0
	v_mov_b32_e32 v70, 0
	v_mov_b32_e32 v71, 0
	v_mov_b32_e32 v72, 0
	v_mov_b32_e32 v73, 0
	v_mov_b32_e32 v74, 0
	v_mov_b32_e32 v75, 0
	v_mov_b32_e32 v76, 0
	v_mov_b32_e32 v77, 0
	v_mov_b32_e32 v78, 0
	v_mov_b32_e32 v79, 0
	v_mov_b32_e32 v80, 0
	v_mov_b32_e32 v81, 0
	v_mov_b32_e32 v82, 0
	v_mov_b32_e32 v83, 0
	v_mov_b32_e32 v84, 0
	v_mov_b32_e32 v85, 0
	v_mov_b32_e32 v86, 0
	v_mov_b32_e32 v87, 0
	v_mov_b32_e32 v88, 0
	v_mov_b32_e32 v89, 0
	v_mov_b32_e32 v90, 0
	v_mov_b32_e32 v91, 0
	v_mov_b32_e32 v92, 0
	v_mov_b32_e32 v93, 0
	v_mov_b32_e32 v94, 0
	v_mov_b32_e32 v95, 0
	v_mov_b32_e32 v96, 0
	v_mov_b32_e32 v97, 0
	v_mov_b32_e32 v98, 0
	v_mov_b32_e32 v99, 0
	v_mov_b32_e32 v100, 0
	v_mov_b32_e32 v101, 0
	v_mov_b32_e32 v102, 0
	v_mov_b32_e32 v103, 0
	v_mov_b32_e32 v104, 0
	v_mov_b32_e32 v105, 0
	v_mov_b32_e32 v134, 0
	v_mov_b32_e32 v135, 0
	v_mov_b32_e32 v136, 0
	v_mov_b32_e32 v137, 0
	v_mov_b32_e32 v138, 0
	v_mov_b32_e32 v139, 0
	v_mov_b32_e32 v140, 0
	v_mov_b32_e32 v141, 0
	v_mov_b32_e32 v142, 0
	v_mov_b32_e32 v143, 0
	v_mov_b32_e32 v144, 0
	v_mov_b32_e32 v145, 0
	v_mov_b32_e32 v146, 0
	v_mov_b32_e32 v147, 0
	v_mov_b32_e32 v148, 0
	v_mov_b32_e32 v149, 0
	v_mov_b32_e32 v150, 0
	v_mov_b32_e32 v151, 0
	v_mov_b32_e32 v152, 0
	v_mov_b32_e32 v153, 0
	v_mov_b32_e32 v154, 0
	v_mov_b32_e32 v155, 0
	v_mov_b32_e32 v156, 0
	v_mov_b32_e32 v157, 0
	v_mov_b32_e32 v158, 0
	v_mov_b32_e32 v159, 0
	v_mov_b32_e32 v160, 0
	v_mov_b32_e32 v161, 0
	v_mov_b32_e32 v162, 0
	v_mov_b32_e32 v163, 0
	v_mov_b32_e32 v164, 0
	v_mov_b32_e32 v165, 0
	v_mov_b32_e32 v166, 0
	v_mov_b32_e32 v167, 0
	v_mov_b32_e32 v168, 0
	v_mov_b32_e32 v169, 0
	v_mov_b32_e32 v170, 0
	v_mov_b32_e32 v171, 0
	v_mov_b32_e32 v172, 0
	v_mov_b32_e32 v173, 0
	v_mov_b32_e32 v174, 0
	v_mov_b32_e32 v175, 0
	v_mov_b32_e32 v176, 0
	v_mov_b32_e32 v177, 0
	v_mov_b32_e32 v178, 0
	v_mov_b32_e32 v179, 0
	v_mov_b32_e32 v180, 0
	v_mov_b32_e32 v181, 0
	v_mov_b32_e32 v182, 0
	v_mov_b32_e32 v183, 0
	v_mov_b32_e32 v184, 0
	v_mov_b32_e32 v185, 0
	v_mov_b32_e32 v186, 0
	v_mov_b32_e32 v187, 0
	v_mov_b32_e32 v188, 0
	v_mov_b32_e32 v189, 0
	v_mov_b32_e32 v190, 0
	v_mov_b32_e32 v191, 0
	v_mov_b32_e32 v192, 0
	v_mov_b32_e32 v193, 0
	v_mov_b32_e32 v194, 0
	v_mov_b32_e32 v195, 0
	v_mov_b32_e32 v196, 0
	v_mov_b32_e32 v197, 0
	s_waitcnt vmcnt(6)
	v_lshl_or_b32 v235, v0, 12, v2
	v_or3_b32 v236, v3, v2, s8
	s_waitcnt lgkmcnt(0)
	s_barrier
	ds_read_b128 v[14:17], v235
	ds_read_b128 v[10:13], v235 offset:1024
	ds_read_b128 v[6:9], v235 offset:2048
	ds_read_b128 v[2:5], v235 offset:3072
	ds_read_b128 v[26:29], v236
	ds_read_b128 v[18:21], v236 offset:1024
	v_cmp_lt_i32_e32 vcc, 3, v230
	s_and_saveexec_b64 s[20:21], vcc
	s_cbranch_execz .LBB0_407
.LBB0_407:
	s_or_b64 exec, exec, s[20:21]
	v_readlane_b32 s8, v254, 46
	v_mov_b32_e32 v24, v1
	v_mov_b32_e32 v25, v1
	v_lshl_add_u32 v233, v0, 6, s8
	v_lshrrev_b32_e32 v0, 4, v233
	s_movk_i32 s8, 0xc0
	v_mul_lo_u32 v238, v0, s8
	v_lshlrev_b32_e32 v0, 3, v200
	v_mov_b32_e32 v22, v1
	v_mov_b32_e32 v23, v1
	v_mov_b32_e32 v30, 0
	v_mov_b32_e32 v42, 0
	v_mov_b64_e32 v[36:37], v[24:25]
	v_add_u32_e32 v237, 0x800, v236
	v_or_b32_e32 v239, 0xc0, v238
	v_add_u32_e32 v240, 0x180, v238
	v_add_u32_e32 v241, 0x240, v238
	s_mov_b32 s8, 3
	v_lshl_add_u64 v[132:133], s[46:47], 0, v[0:1]
	s_mov_b64 s[20:21], 0
	v_mov_b64_e32 v[34:35], v[22:23]
	s_branch .LBB0_409

.LBB0_415:
	s_waitcnt lgkmcnt(0)
	s_add_i32 s19, s8, -2
	s_and_b32 s29, s19, 3
	s_mulk_i32 s29, 0x6000
	v_add_u32_e32 v127, s29, v235
	v_add_u32_e32 v226, s29, v236
	ds_read_b128 v[26:29], v226
	v_mfma_f32_16x16x32_bf16 v[90:93], v[14:17], v[106:109], v[90:93]
	ds_read_b128 v[18:21], v226 offset:1024
	v_mfma_f32_16x16x32_bf16 v[74:77], v[10:13], v[106:109], v[74:77]
	ds_read_b128 v[118:121], v127
	v_mfma_f32_16x16x32_bf16 v[58:61], v[6:9], v[106:109], v[58:61]
	ds_read_b128 v[114:117], v127 offset:1024
	v_mfma_f32_16x16x32_bf16 v[46:49], v[2:5], v[106:109], v[46:49]
	ds_read_b128 v[110:113], v127 offset:2048
	ds_read_b128 v[106:109], v127 offset:3072
	v_mfma_f32_16x16x32_bf16 v[94:97], v[14:17], v[242:245], v[94:97]
	v_mfma_f32_16x16x32_bf16 v[78:81], v[10:13], v[242:245], v[78:81]
	v_mfma_f32_16x16x32_bf16 v[62:65], v[6:9], v[242:245], v[62:65]
	v_mfma_f32_16x16x32_bf16 v[42:45], v[2:5], v[242:245], v[42:45]
	s_mov_b64 s[26:27], -1
	s_and_b64 vcc, exec, s[24:25]
	s_cbranch_vccz .LBB0_417
	s_waitcnt vmcnt(0)
	s_mov_b64 s[26:27], 0

.LBB0_421:
	s_waitcnt lgkmcnt(0)
	v_mfma_f32_16x16x32_bf16 v[90:93], v[118:121], v[242:245], v[90:93]
	v_mfma_f32_16x16x32_bf16 v[74:77], v[114:117], v[242:245], v[74:77]
	v_mfma_f32_16x16x32_bf16 v[58:61], v[110:113], v[242:245], v[58:61]
	v_mfma_f32_16x16x32_bf16 v[46:49], v[106:109], v[242:245], v[46:49]
	s_andn2_b64 vcc, exec, s[22:23]
	s_cbranch_vccnz .LBB0_423
	s_add_i32 s22, s8, -1
	s_and_b32 s22, s22, 2
	s_mulk_i32 s22, 0x6000
	v_add_u32_e32 v18, s22, v235
	ds_read_b128 v[14:17], v18
	ds_read_b128 v[10:13], v18 offset:1024
	ds_read_b128 v[6:9], v18 offset:2048
	ds_read_b128 v[2:5], v18 offset:3072
	v_add_u32_e32 v198, s22, v236
	ds_read_b128 v[26:29], v198
	ds_read_b128 v[18:21], v198 offset:1024

.LBB0_425:
	v_cmp_gt_i32_e32 vcc, 4, v230
	s_and_saveexec_b64 s[20:21], vcc
	s_cbranch_execz .LBB0_427
.LBB0_427:
	s_or_b64 exec, exec, s[20:21]
	s_movk_i32 s8, 0x4400
	v_mul_lo_u32 v2, v230, s8
	v_lshl_or_b32 v3, v234, 2, v2
	s_movk_i32 s8, 0x440
	v_mad_u32_u24 v3, v201, s8, v3
	v_add_u32_e32 v4, 0x1000, v3
	v_add_u32_e32 v5, 0x1400, v3
	s_waitcnt vmcnt(0) lgkmcnt(0)
	s_barrier
	ds_write2_b32 v3, v196, v192 offset1:16
	ds_write2_b32 v3, v197, v193 offset0:68 offset1:84
	ds_write2_b32 v3, v194, v190 offset0:136 offset1:152
	ds_write2_b32 v3, v195, v191 offset0:204 offset1:220
	ds_write2_b32 v3, v188, v184 offset0:32 offset1:48
	ds_write2_b32 v3, v189, v185 offset0:100 offset1:116
	ds_write2_b32 v3, v186, v182 offset0:168 offset1:184
	ds_write2_b32 v3, v187, v183 offset0:236 offset1:252
	ds_write2_b32 v4, v180, v176 offset0:64 offset1:80
	ds_write2_b32 v4, v181, v177 offset0:132 offset1:148
	ds_write2_b32 v4, v178, v174 offset0:200 offset1:216
	ds_write2_b32 v5, v179, v175 offset0:12 offset1:28
	ds_write2_b32 v4, v172, v168 offset0:96 offset1:112
	ds_write2_b32 v4, v173, v169 offset0:164 offset1:180
	ds_write2_b32 v4, v170, v166 offset0:232 offset1:248
	ds_write2_b32 v5, v171, v167 offset0:44 offset1:60
	v_add_u32_e32 v4, 0x2000, v3
	v_add_u32_e32 v5, 0x2400, v3
	ds_write2_b32 v4, v164, v160 offset0:128 offset1:144
	ds_write2_b32 v4, v165, v161 offset0:196 offset1:212
	ds_write2_b32 v5, v162, v158 offset0:8 offset1:24
	ds_write2_b32 v5, v163, v159 offset0:76 offset1:92
	ds_write2_b32 v4, v156, v152 offset0:160 offset1:176
	ds_write2_b32 v4, v157, v153 offset0:228 offset1:244
	ds_write2_b32 v5, v154, v150 offset0:40 offset1:56
	ds_write2_b32 v5, v155, v151 offset0:108 offset1:124
	v_add_u32_e32 v4, 0x3000, v3
	v_add_u32_e32 v3, 0x3400, v3
	v_lshrrev_b32_e32 v12, 3, v200
	v_and_b32_e32 v0, 56, v0
	ds_write2_b32 v4, v148, v144 offset0:192 offset1:208
	ds_write2_b32 v3, v149, v145 offset0:4 offset1:20
	ds_write2_b32 v3, v146, v142 offset0:72 offset1:88
	ds_write2_b32 v3, v147, v143 offset0:140 offset1:156
	ds_write2_b32 v4, v140, v136 offset0:224 offset1:240
	ds_write2_b32 v3, v141, v137 offset0:36 offset1:52
	ds_write2_b32 v3, v138, v134 offset0:104 offset1:120
	ds_write2_b32 v3, v139, v135 offset0:172 offset1:188
	v_mul_u32_u24_e32 v3, 0x110, v12
	v_lshlrev_b32_e32 v4, 2, v0
	v_add3_u32 v20, v2, v3, v4
	ds_read_b128 v[2:5], v20
	ds_read_b128 v[6:9], v20 offset:16
	v_readlane_b32 s8, v254, 47
	s_lshl_b32 s8, s8, 1
	v_readlane_b32 s20, v254, 49
	v_or_b32_e32 v16, v233, v12
	v_lshl_or_b32 v10, v231, 7, s8
	v_mov_b32_e32 v11, v1
	v_readlane_b32 s21, v254, 50
	v_ashrrev_i32_e32 v17, 31, v16
	s_waitcnt lgkmcnt(1)
	v_cvt_pk_bf16_f32 v2, v2, v3
	v_lshl_add_u64 v[14:15], s[20:21], 0, v[10:11]
	v_cvt_pk_bf16_f32 v3, v4, v5
	s_waitcnt lgkmcnt(0)
	v_cvt_pk_bf16_f32 v4, v6, v7
	v_lshlrev_b64 v[6:7], 11, v[16:17]
	v_cvt_pk_bf16_f32 v5, v8, v9
	v_lshl_add_u64 v[18:19], v[14:15], 0, v[6:7]
	ds_read_b128 v[6:9], v20 offset:2176
	ds_read_b128 v[10:13], v20 offset:2192
	v_lshlrev_b32_e32 v0, 1, v0
	v_lshl_add_u64 v[18:19], v[18:19], 0, v[0:1]
	global_store_dwordx4 v[18:19], v[2:5], off
	s_waitcnt lgkmcnt(1)
	s_nop 0
	v_cvt_pk_bf16_f32 v2, v6, v7
	v_or_b32_e32 v6, 8, v16
	v_ashrrev_i32_e32 v7, 31, v6
	v_cvt_pk_bf16_f32 v3, v8, v9
	s_waitcnt lgkmcnt(0)
	v_cvt_pk_bf16_f32 v4, v10, v11
	v_lshlrev_b64 v[10:11], 11, v[6:7]
	ds_read_b128 v[6:9], v20 offset:4352
	v_cvt_pk_bf16_f32 v5, v12, v13
	v_lshl_add_u64 v[18:19], v[14:15], 0, v[10:11]
	ds_read_b128 v[10:13], v20 offset:4368
	v_lshl_add_u64 v[18:19], v[18:19], 0, v[0:1]
	global_store_dwordx4 v[18:19], v[2:5], off
	s_waitcnt lgkmcnt(1)
	s_nop 0
	v_cvt_pk_bf16_f32 v2, v6, v7
	v_or_b32_e32 v6, 16, v16
	v_ashrrev_i32_e32 v7, 31, v6
	v_cvt_pk_bf16_f32 v3, v8, v9
	s_waitcnt lgkmcnt(0)
	v_cvt_pk_bf16_f32 v4, v10, v11
	v_lshlrev_b64 v[10:11], 11, v[6:7]
	ds_read_b128 v[6:9], v20 offset:6528
	v_cvt_pk_bf16_f32 v5, v12, v13
	v_lshl_add_u64 v[18:19], v[14:15], 0, v[10:11]
	ds_read_b128 v[10:13], v20 offset:6544
	v_lshl_add_u64 v[18:19], v[18:19], 0, v[0:1]
	global_store_dwordx4 v[18:19], v[2:5], off
	s_waitcnt lgkmcnt(1)
	s_nop 0
	v_cvt_pk_bf16_f32 v2, v6, v7
	v_or_b32_e32 v6, 24, v16
	v_ashrrev_i32_e32 v7, 31, v6
	v_cvt_pk_bf16_f32 v3, v8, v9
	s_waitcnt lgkmcnt(0)
	v_cvt_pk_bf16_f32 v4, v10, v11
	v_lshlrev_b64 v[10:11], 11, v[6:7]
	ds_read_b128 v[6:9], v20 offset:8704
	v_cvt_pk_bf16_f32 v5, v12, v13
	v_lshl_add_u64 v[18:19], v[14:15], 0, v[10:11]
	ds_read_b128 v[10:13], v20 offset:8720
	v_lshl_add_u64 v[18:19], v[18:19], 0, v[0:1]
	global_store_dwordx4 v[18:19], v[2:5], off
	s_waitcnt lgkmcnt(1)
	s_nop 0
	v_cvt_pk_bf16_f32 v2, v6, v7
	v_or_b32_e32 v6, 32, v16
	v_ashrrev_i32_e32 v7, 31, v6
	v_cvt_pk_bf16_f32 v3, v8, v9
	s_waitcnt lgkmcnt(0)
	v_cvt_pk_bf16_f32 v4, v10, v11
	v_lshlrev_b64 v[10:11], 11, v[6:7]
	ds_read_b128 v[6:9], v20 offset:10880
	v_cvt_pk_bf16_f32 v5, v12, v13
	v_lshl_add_u64 v[18:19], v[14:15], 0, v[10:11]
	ds_read_b128 v[10:13], v20 offset:10896
	v_lshl_add_u64 v[18:19], v[18:19], 0, v[0:1]
	global_store_dwordx4 v[18:19], v[2:5], off
	s_waitcnt lgkmcnt(1)
	s_nop 0
	v_cvt_pk_bf16_f32 v2, v6, v7
	v_or_b32_e32 v6, 40, v16
	v_ashrrev_i32_e32 v7, 31, v6
	v_cvt_pk_bf16_f32 v3, v8, v9
	s_waitcnt lgkmcnt(0)
	v_cvt_pk_bf16_f32 v4, v10, v11
	v_lshlrev_b64 v[10:11], 11, v[6:7]
	ds_read_b128 v[6:9], v20 offset:13056
	v_cvt_pk_bf16_f32 v5, v12, v13
	v_lshl_add_u64 v[18:19], v[14:15], 0, v[10:11]
	ds_read_b128 v[10:13], v20 offset:13072
	v_lshl_add_u64 v[18:19], v[18:19], 0, v[0:1]
	global_store_dwordx4 v[18:19], v[2:5], off
	s_waitcnt lgkmcnt(1)
	s_nop 0
	v_cvt_pk_bf16_f32 v2, v6, v7
	v_or_b32_e32 v6, 48, v16
	v_ashrrev_i32_e32 v7, 31, v6
	v_cvt_pk_bf16_f32 v3, v8, v9
	s_waitcnt lgkmcnt(0)
	v_cvt_pk_bf16_f32 v4, v10, v11
	v_lshlrev_b64 v[10:11], 11, v[6:7]
	ds_read_b128 v[6:9], v20 offset:15232
	v_lshl_add_u64 v[18:19], v[14:15], 0, v[10:11]
	v_cvt_pk_bf16_f32 v5, v12, v13
	ds_read_b128 v[10:13], v20 offset:15248
	v_lshl_add_u64 v[18:19], v[18:19], 0, v[0:1]
	global_store_dwordx4 v[18:19], v[2:5], off
	s_waitcnt lgkmcnt(1)
	s_nop 0
	v_cvt_pk_bf16_f32 v2, v6, v7
	v_or_b32_e32 v6, 56, v16
	v_ashrrev_i32_e32 v7, 31, v6
	v_lshlrev_b64 v[6:7], 11, v[6:7]
	v_lshl_add_u64 v[6:7], v[14:15], 0, v[6:7]
	v_cvt_pk_bf16_f32 v3, v8, v9
	s_waitcnt lgkmcnt(0)
	v_cvt_pk_bf16_f32 v4, v10, v11
	v_cvt_pk_bf16_f32 v5, v12, v13
	v_lshl_add_u64 v[6:7], v[6:7], 0, v[0:1]
	global_store_dwordx4 v[6:7], v[2:5], off
